# full stack: tile-start restructure + barrier waiters poll arrival counter + final-epilogue wait ladder + GELU fold + K/Q epilogue trims
# speedup vs baseline: 1.0051x; 1.0051x over previous
.LBB0_207:
	s_add_u32 s50, s54, 0xc000000
	s_addc_u32 s51, s55, 0
	s_lshl_b32 s5, s5, 5
	s_mov_b64 s[12:13], 0x80
	s_and_b32 s5, s5, 0x60
	s_add_i32 m0, s31, 0x18000
	v_lshl_add_u64 v[6:7], v[6:7], 0, s[12:13]
	s_lshl_b32 s7, s4, 13
	s_lshl_b32 s15, s5, 7
	s_waitcnt vmcnt(2)
	s_barrier
	global_load_lds_dwordx4 v[6:7], off
	v_lshl_add_u64 v[2:3], v[2:3], 0, s[12:13]
	s_add_i32 m0, s31, 0x1a000
	s_add_i32 s60, s31, 0x8000
	s_add_i32 s61, s31, 0xa000
	global_load_lds_dwordx4 v[2:3], off
	v_lshl_add_u64 v[0:1], v[0:1], 0, s[12:13]
	s_mov_b32 m0, s60
	s_add_u32 s16, s36, 0x40080
	global_load_lds_dwordx4 v[0:1], off
	v_lshl_add_u64 v[0:1], v[4:5], 0, s[12:13]
	s_mov_b32 m0, s61
	s_addc_u32 s17, s37, 0
	global_load_lds_dwordx4 v[0:1], off
	s_add_i32 m0, s31, 0x1c000
	v_lshl_add_u64 v[0:1], s[16:17], 0, v[130:131]
	global_load_lds_dwordx4 v[0:1], off
	v_lshl_add_u64 v[0:1], s[16:17], 0, v[134:135]
	s_add_i32 m0, s31, 0x1e000
	s_cmpk_lt_u32 s14, 0x100
	global_load_lds_dwordx4 v[0:1], off
	v_lshrrev_b32_e32 v1, 1, v8
	v_and_b32_e32 v1, 24, v1
	v_and_b32_e32 v0, 15, v8
	v_lshlrev_b32_e32 v2, 1, v1
	v_lshl_or_b32 v152, s4, 6, v0
	v_lshl_or_b32 v0, v0, 6, v2
	v_lshlrev_b32_e32 v2, 2, v8
	v_and_b32_e32 v2, 32, v2
	v_bitop3_b32 v3, v0, s7, v2 bitop3:0xde
	v_bitop3_b32 v153, v0, s15, v2 bitop3:0xde
	v_lshlrev_b32_e32 v0, 14, v9
	v_and_b32_e32 v0, 0xffff8000, v0
	v_or_b32_e32 v154, s5, v1
	v_lshl_add_u32 v0, v10, 11, v0
	v_and_b32_e32 v1, 1, v9
	v_lshl_or_b32 v0, v1, 6, v0
	v_lshl_add_u32 v138, v11, 1, v0
	v_lshlrev_b32_e32 v0, 14, v12
	v_and_b32_e32 v0, 0xffff8000, v0
	s_waitcnt vmcnt(6)
	v_lshl_add_u32 v0, v13, 11, v0
	v_and_b32_e32 v1, 1, v12
	s_cselect_b64 s[14:15], -1, 0
	v_lshl_or_b32 v0, v1, 6, v0
	s_add_i32 s65, 0, 0x10000
	s_add_i32 s67, 0, 0x14000
	s_ashr_i32 s62, s52, 31
	s_mov_b32 s63, s52
	s_ashr_i32 s64, s33, 31
	v_mov_b32_e32 v139, v137
	v_lshl_add_u32 v140, v14, 1, v0
	v_mov_b32_e32 v141, v137
	v_mov_b64_e32 v[142:143], 0x400
	v_mov_b64_e32 v[144:145], 0x3ff
	v_add_u32_e32 v155, s65, v153
	v_add_u32_e32 v156, s67, v153
	v_add_u32_e32 v157, 0, v3
	s_mov_b64 s[16:17], 0x48000
	s_mov_b64 s[18:19], 0x50000
	s_mov_b64 s[20:21], 0x58000
	s_barrier
	s_mov_b32 s101, 0
	v_mov_b32_e32 v254, 0xbdd2d3e7
	s_branch .LBB0_210
